# e23: s_nop pads in cold code so that the GEMM and attention hot loops have the fewest 8-byte instructions straddling 64-byte fetch lines
# speedup vs baseline: 1.0096x; 1.0096x over previous
; template <class Epi, class Sched, bool ALIGN_EPI = false, bool SP2 = false>
; __device__ __forceinline__ void gemm_phase(PG8_LAS unsigned char* lds, const Gemm g, const Sched& S, const Epi& E) {
;     ...
;         const bool has_next = S.next(ui + 1, nxt);
;         const char* nA = has_next ? PG8_UA(nxt) : cA; const char* nB = has_next ? PG8_UB(nxt) : cB;
;         for (int t = 0; t < nt; t += 2) {
;             const bool last = (t == nt - 2);
;             const char* a1 = cA + (size_t)(t + 1) * kstep;
;             const char* a2 = last ? nA : cA + (size_t)(t + 2) * kstep; const char* b2 = last ? nB : cB + (size_t)(t + 2) * kstep;
;             const char* a3 = a2 + kstep; const char* b3 = b2 + kstep;
;     ...
; #pragma unroll
;         for (int a = 0; a < 2; ++a)
; #pragma unroll
;             for (int b = 0; b < 2; ++b)
; #pragma unroll
;                 for (int m = 0; m < 4; ++m)
; #pragma unroll
;                     for (int n = 0; n < 2; ++n) acc[a][b][m][n] = (f32x4){0.f, 0.f, 0.f, 0.f};
.LBB0_203:
	s_ashr_i32 s43, s42, 31
	s_lshl_b64 s[4:5], s[42:43], 20
	s_add_u32 s48, s67, s4
	s_addc_u32 s49, s77, s5
	s_and_b64 s[4:5], s[38:39], exec
	s_cselect_b32 s4, s49, s37
	s_cselect_b32 s5, s48, s36
	s_ashr_i32 s21, s20, 31
	s_lshl_b64 s[6:7], s[20:21], 20
	s_add_u32 s50, s0, s6
	s_addc_u32 s51, s1, s7
	s_and_b64 s[6:7], s[38:39], exec
	s_cselect_b32 s6, s51, s57
	s_cselect_b32 s7, s50, s56
	s_add_u32 s36, s36, 0x80080
	s_addc_u32 s37, s37, 0
	s_add_u32 s21, s56, 0x100
	v_mov_b32_e32 v4, 0
	s_addc_u32 s41, s57, 0
	s_mov_b32 s43, -2
	v_mov_b32_e32 v5, v4
	v_mov_b32_e32 v6, v4
	v_mov_b32_e32 v7, v4
	v_mov_b32_e32 v8, v4
	v_mov_b32_e32 v9, v4
	v_mov_b32_e32 v10, v4
	v_mov_b32_e32 v11, v4
	v_mov_b32_e32 v20, v4
	v_mov_b32_e32 v21, v4
	v_mov_b32_e32 v22, v4
	v_mov_b32_e32 v23, v4
	v_mov_b32_e32 v24, v4
	v_mov_b32_e32 v25, v4
	v_mov_b32_e32 v26, v4
	v_mov_b32_e32 v27, v4
	v_mov_b32_e32 v36, v4
	v_mov_b32_e32 v37, v4
	v_mov_b32_e32 v38, v4
	v_mov_b32_e32 v39, v4
	v_mov_b32_e32 v40, v4
	v_mov_b32_e32 v41, v4
	v_mov_b32_e32 v42, v4
	v_mov_b32_e32 v43, v4
	v_mov_b32_e32 v52, v4
	v_mov_b32_e32 v53, v4
	v_mov_b32_e32 v54, v4
	v_mov_b32_e32 v55, v4
	v_mov_b32_e32 v56, v4
	v_mov_b32_e32 v57, v4
	v_mov_b32_e32 v58, v4
	v_mov_b32_e32 v59, v4
	v_mov_b32_e32 v12, v4
	v_mov_b32_e32 v13, v4
	v_mov_b32_e32 v14, v4
	v_mov_b32_e32 v15, v4
	v_mov_b32_e32 v16, v4
	v_mov_b32_e32 v17, v4
	v_mov_b32_e32 v18, v4
	v_mov_b32_e32 v19, v4
	v_mov_b32_e32 v28, v4
	v_mov_b32_e32 v29, v4
	v_mov_b32_e32 v30, v4
	v_mov_b32_e32 v31, v4
	v_mov_b32_e32 v32, v4
	v_mov_b32_e32 v33, v4
	v_mov_b32_e32 v34, v4
	v_mov_b32_e32 v35, v4
	v_mov_b32_e32 v44, v4
	v_mov_b32_e32 v45, v4
	v_mov_b32_e32 v46, v4
	v_mov_b32_e32 v47, v4
	v_mov_b32_e32 v48, v4
	v_mov_b32_e32 v49, v4
	v_mov_b32_e32 v50, v4
	v_mov_b32_e32 v51, v4
	v_mov_b32_e32 v60, v4
	v_mov_b32_e32 v61, v4
	v_mov_b32_e32 v62, v4
	v_mov_b32_e32 v63, v4
	v_mov_b32_e32 v64, v4
	v_mov_b32_e32 v65, v4
	v_mov_b32_e32 v66, v4
	v_mov_b32_e32 v67, v4
	v_mov_b32_e32 v68, v4
	v_mov_b32_e32 v69, v4
	v_mov_b32_e32 v70, v4
	v_mov_b32_e32 v71, v4
	v_mov_b32_e32 v72, v4
	v_mov_b32_e32 v73, v4
	v_mov_b32_e32 v74, v4
	v_mov_b32_e32 v75, v4
	v_mov_b32_e32 v84, v4
	v_mov_b32_e32 v85, v4
	v_mov_b32_e32 v86, v4
	v_mov_b32_e32 v87, v4
	v_mov_b32_e32 v88, v4
	v_mov_b32_e32 v89, v4
	v_mov_b32_e32 v90, v4
	v_mov_b32_e32 v91, v4
	v_mov_b32_e32 v100, v4
	v_mov_b32_e32 v101, v4
	v_mov_b32_e32 v102, v4
	v_mov_b32_e32 v103, v4
	v_mov_b32_e32 v104, v4
	v_mov_b32_e32 v105, v4
	v_mov_b32_e32 v106, v4
	v_mov_b32_e32 v107, v4
	v_mov_b32_e32 v116, v4
	v_mov_b32_e32 v117, v4
	v_mov_b32_e32 v118, v4
	v_mov_b32_e32 v119, v4
	v_mov_b32_e32 v120, v4
	v_mov_b32_e32 v121, v4
	v_mov_b32_e32 v122, v4
	v_mov_b32_e32 v123, v4
	v_mov_b32_e32 v76, v4
	v_mov_b32_e32 v77, v4
	v_mov_b32_e32 v78, v4
	v_mov_b32_e32 v79, v4
	v_mov_b32_e32 v80, v4
	v_mov_b32_e32 v81, v4
	v_mov_b32_e32 v82, v4
	v_mov_b32_e32 v83, v4
	v_mov_b32_e32 v92, v4
	v_mov_b32_e32 v93, v4
	v_mov_b32_e32 v94, v4
	v_mov_b32_e32 v95, v4
	v_mov_b32_e32 v96, v4
	v_mov_b32_e32 v97, v4
	v_mov_b32_e32 v98, v4
	v_mov_b32_e32 v99, v4
	v_mov_b32_e32 v108, v4
	v_mov_b32_e32 v109, v4
	v_mov_b32_e32 v110, v4
	v_mov_b32_e32 v111, v4
	v_mov_b32_e32 v112, v4
	v_mov_b32_e32 v113, v4
	v_mov_b32_e32 v114, v4
	v_mov_b32_e32 v115, v4
	v_mov_b32_e32 v124, v4
	v_mov_b32_e32 v125, v4
	v_mov_b32_e32 v126, v4
	v_mov_b32_e32 v127, v4
	v_mov_b32_e32 v128, v4
	v_mov_b32_e32 v129, v4
	v_mov_b32_e32 v130, v4
	v_mov_b32_e32 v131, v4
	s_nop 0

; __global__ void __launch_bounds__(512, 2) fwd_kernel(Args a) {
;     ...
;                 for (int p = vcu; p < 1024; p += G) { const int hc = p >> 6, pr = p & 63, h = hc & 7, c = hc >> 3;
; #pragma unroll 1
;                     for (int which = 0; which < 2; ++which) { const int qb = which ? pr : 127 - pr;
;                         att::attn_unit2(A0 + (size_t)qb * 128 * D + h * 256 + c * 128, Kb + h * 256 + c * 128, A2 + h * 256,
;                                         A3 + (size_t)c * M * D + (size_t)qb * 128 * D + h * 256, 2 * qb + 2, 2 * qb + ((wave & 3) >> 1), 128 * qb + 32 * (wave & 3), lut + h * 256, ldsg, scr);
;                         __syncthreads(); } } }
.LBB0_424:
	s_add_i32 s48, s48, s49
	s_add_i32 s64, s64, s65
	s_cmpk_gt_i32 s48, 0x3ff
	s_cbranch_scc1 .LBB0_458
	s_nop 0

; template <class Epi, class Sched, bool ALIGN_EPI = false, bool SP2 = false>
; __device__ __forceinline__ void gemm_phase(PG8_LAS unsigned char* lds, const Gemm g, const Sched& S, const Epi& E) {
;     ...
;         const bool has_next = S.next(ui + 1, nxt);
;         const char* nA = has_next ? PG8_UA(nxt) : cA; const char* nB = has_next ? PG8_UB(nxt) : cB;
;         for (int t = 0; t < nt; t += 2) {
;             const bool last = (t == nt - 2);
;             const char* a1 = cA + (size_t)(t + 1) * kstep;
;             const char* a2 = last ? nA : cA + (size_t)(t + 2) * kstep; const char* b2 = last ? nB : cB + (size_t)(t + 2) * kstep;
;             const char* a3 = a2 + kstep; const char* b3 = b2 + kstep;
;     ...
; #pragma unroll
;         for (int a = 0; a < 2; ++a)
; #pragma unroll
;             for (int b = 0; b < 2; ++b)
; #pragma unroll
;                 for (int m = 0; m < 4; ++m)
; #pragma unroll
;                     for (int n = 0; n < 2; ++n) acc[a][b][m][n] = (f32x4){0.f, 0.f, 0.f, 0.f};
.LBB0_1759:
	s_ashr_i32 s53, s52, 31
	s_lshl_b64 s[4:5], s[52:53], 18
	s_add_u32 s64, s18, s4
	s_addc_u32 s65, s19, s5
	s_and_b64 s[4:5], s[42:43], exec
	s_cselect_b32 s4, s65, s67
	s_cselect_b32 s5, s64, s66
	s_add_u32 s42, s62, 0x80080
	s_addc_u32 s43, s63, 0
	s_add_u32 s6, s66, 0x100
	v_mov_b32_e32 v4, 0
	s_addc_u32 s7, s67, 0
	s_mov_b32 s21, -2
	s_waitcnt lgkmcnt(0)
	v_mov_b32_e32 v5, v4
	v_mov_b32_e32 v6, v4
	v_mov_b32_e32 v7, v4
	v_mov_b32_e32 v8, v4
	v_mov_b32_e32 v9, v4
	v_mov_b32_e32 v10, v4
	v_mov_b32_e32 v11, v4
	v_mov_b32_e32 v20, v4
	v_mov_b32_e32 v21, v4
	v_mov_b32_e32 v22, v4
	v_mov_b32_e32 v23, v4
	v_mov_b32_e32 v24, v4
	v_mov_b32_e32 v25, v4
	v_mov_b32_e32 v26, v4
	v_mov_b32_e32 v27, v4
	v_mov_b32_e32 v36, v4
	v_mov_b32_e32 v37, v4
	v_mov_b32_e32 v38, v4
	v_mov_b32_e32 v39, v4
	v_mov_b32_e32 v40, v4
	v_mov_b32_e32 v41, v4
	v_mov_b32_e32 v42, v4
	v_mov_b32_e32 v43, v4
	v_mov_b32_e32 v52, v4
	v_mov_b32_e32 v53, v4
	v_mov_b32_e32 v54, v4
	v_mov_b32_e32 v55, v4
	v_mov_b32_e32 v56, v4
	v_mov_b32_e32 v57, v4
	v_mov_b32_e32 v58, v4
	v_mov_b32_e32 v59, v4
	v_mov_b32_e32 v12, v4
	v_mov_b32_e32 v13, v4
	v_mov_b32_e32 v14, v4
	v_mov_b32_e32 v15, v4
	v_mov_b32_e32 v16, v4
	v_mov_b32_e32 v17, v4
	v_mov_b32_e32 v18, v4
	v_mov_b32_e32 v19, v4
	v_mov_b32_e32 v28, v4
	v_mov_b32_e32 v29, v4
	v_mov_b32_e32 v30, v4
	v_mov_b32_e32 v31, v4
	v_mov_b32_e32 v32, v4
	v_mov_b32_e32 v33, v4
	v_mov_b32_e32 v34, v4
	v_mov_b32_e32 v35, v4
	v_mov_b32_e32 v44, v4
	v_mov_b32_e32 v45, v4
	v_mov_b32_e32 v46, v4
	v_mov_b32_e32 v47, v4
	v_mov_b32_e32 v48, v4
	v_mov_b32_e32 v49, v4
	v_mov_b32_e32 v50, v4
	v_mov_b32_e32 v51, v4
	v_mov_b32_e32 v60, v4
	v_mov_b32_e32 v61, v4
	v_mov_b32_e32 v62, v4
	v_mov_b32_e32 v63, v4
	v_mov_b32_e32 v64, v4
	v_mov_b32_e32 v65, v4
	v_mov_b32_e32 v66, v4
	v_mov_b32_e32 v67, v4
	v_mov_b32_e32 v68, v4
	v_mov_b32_e32 v69, v4
	v_mov_b32_e32 v70, v4
	v_mov_b32_e32 v71, v4
	v_mov_b32_e32 v72, v4
	v_mov_b32_e32 v73, v4
	v_mov_b32_e32 v74, v4
	v_mov_b32_e32 v75, v4
	v_mov_b32_e32 v100, v4
	v_mov_b32_e32 v101, v4
	v_mov_b32_e32 v102, v4
	v_mov_b32_e32 v103, v4
	v_mov_b32_e32 v104, v4
	v_mov_b32_e32 v105, v4
	v_mov_b32_e32 v106, v4
	v_mov_b32_e32 v107, v4
	v_mov_b32_e32 v116, v4
	v_mov_b32_e32 v117, v4
	v_mov_b32_e32 v118, v4
	v_mov_b32_e32 v119, v4
	v_mov_b32_e32 v120, v4
	v_mov_b32_e32 v121, v4
	v_mov_b32_e32 v122, v4
	v_mov_b32_e32 v123, v4
	v_mov_b32_e32 v132, v4
	v_mov_b32_e32 v133, v4
	v_mov_b32_e32 v134, v4
	v_mov_b32_e32 v135, v4
	v_mov_b32_e32 v136, v4
	v_mov_b32_e32 v137, v4
	v_mov_b32_e32 v138, v4
	v_mov_b32_e32 v139, v4
	v_mov_b32_e32 v92, v4
	v_mov_b32_e32 v93, v4
	v_mov_b32_e32 v94, v4
	v_mov_b32_e32 v95, v4
	v_mov_b32_e32 v96, v4
	v_mov_b32_e32 v97, v4
	v_mov_b32_e32 v98, v4
	v_mov_b32_e32 v99, v4
	v_mov_b32_e32 v108, v4
	v_mov_b32_e32 v109, v4
	v_mov_b32_e32 v110, v4
	v_mov_b32_e32 v111, v4
	v_mov_b32_e32 v112, v4
	v_mov_b32_e32 v113, v4
	v_mov_b32_e32 v114, v4
	v_mov_b32_e32 v115, v4
	v_mov_b32_e32 v124, v4
	v_mov_b32_e32 v125, v4
	v_mov_b32_e32 v126, v4
	v_mov_b32_e32 v127, v4
	v_mov_b32_e32 v128, v4
	v_mov_b32_e32 v129, v4
	v_mov_b32_e32 v130, v4
	v_mov_b32_e32 v131, v4
	v_mov_b32_e32 v140, v4
	v_mov_b32_e32 v141, v4
	v_mov_b32_e32 v142, v4
	v_mov_b32_e32 v143, v4
	v_mov_b32_e32 v144, v4
	v_mov_b32_e32 v145, v4
	v_mov_b32_e32 v146, v4
	v_mov_b32_e32 v147, v4
	s_nop 0
	s_nop 0

; template <class Epi, class Sched, bool ALIGN_EPI = false, bool SP2 = false>
; __device__ __forceinline__ void gemm_phase(PG8_LAS unsigned char* lds, const Gemm g, const Sched& S, const Epi& E) {
;     ...
;         const bool has_next = S.next(ui + 1, nxt);
;         const char* nA = has_next ? PG8_UA(nxt) : cA; const char* nB = has_next ? PG8_UB(nxt) : cB;
;         for (int t = 0; t < nt; t += 2) {
;             const bool last = (t == nt - 2);
;             const char* a1 = cA + (size_t)(t + 1) * kstep;
;             const char* a2 = last ? nA : cA + (size_t)(t + 2) * kstep; const char* b2 = last ? nB : cB + (size_t)(t + 2) * kstep;
;             const char* a3 = a2 + kstep; const char* b3 = b2 + kstep;
;     ...
; #pragma unroll
;         for (int a = 0; a < 2; ++a)
; #pragma unroll
;             for (int b = 0; b < 2; ++b)
; #pragma unroll
;                 for (int m = 0; m < 4; ++m)
; #pragma unroll
;                     for (int n = 0; n < 2; ++n) acc[a][b][m][n] = (f32x4){0.f, 0.f, 0.f, 0.f};
.LBB0_1885:
	s_ashr_i32 s53, s52, 31
	s_lshl_b64 s[4:5], s[52:53], 20
	s_add_u32 s56, s78, s4
	s_addc_u32 s57, s79, s5
	s_and_b64 s[4:5], s[38:39], exec
	s_cselect_b32 s3, s57, s37
	s_cselect_b32 s4, s56, s36
	s_ashr_i32 s21, s20, 31
	s_lshl_b64 s[6:7], s[20:21], 20
	s_add_u32 s58, s46, s6
	s_addc_u32 s59, s47, s7
	s_and_b64 s[6:7], s[38:39], exec
	s_cselect_b32 s5, s59, s43
	s_cselect_b32 s6, s58, s42
	s_add_u32 s36, s36, 0x80080
	s_addc_u32 s37, s37, 0
	s_add_u32 s7, s42, 0x100
	v_mov_b32_e32 v4, 0
	s_addc_u32 s21, s43, 0
	s_mov_b32 s41, -2
	v_mov_b32_e32 v5, v4
	v_mov_b32_e32 v6, v4
	v_mov_b32_e32 v7, v4
	v_mov_b32_e32 v8, v4
	v_mov_b32_e32 v9, v4
	v_mov_b32_e32 v10, v4
	v_mov_b32_e32 v11, v4
	v_mov_b32_e32 v20, v4
	v_mov_b32_e32 v21, v4
	v_mov_b32_e32 v22, v4
	v_mov_b32_e32 v23, v4
	v_mov_b32_e32 v28, v4
	v_mov_b32_e32 v29, v4
	v_mov_b32_e32 v30, v4
	v_mov_b32_e32 v31, v4
	v_mov_b32_e32 v52, v4
	v_mov_b32_e32 v53, v4
	v_mov_b32_e32 v54, v4
	v_mov_b32_e32 v55, v4
	v_mov_b32_e32 v56, v4
	v_mov_b32_e32 v57, v4
	v_mov_b32_e32 v58, v4
	v_mov_b32_e32 v59, v4
	v_mov_b32_e32 v68, v4
	v_mov_b32_e32 v69, v4
	v_mov_b32_e32 v70, v4
	v_mov_b32_e32 v71, v4
	v_mov_b32_e32 v72, v4
	v_mov_b32_e32 v73, v4
	v_mov_b32_e32 v74, v4
	v_mov_b32_e32 v75, v4
	v_mov_b32_e32 v12, v4
	v_mov_b32_e32 v13, v4
	v_mov_b32_e32 v14, v4
	v_mov_b32_e32 v15, v4
	v_mov_b32_e32 v16, v4
	v_mov_b32_e32 v17, v4
	v_mov_b32_e32 v18, v4
	v_mov_b32_e32 v19, v4
	v_mov_b32_e32 v40, v4
	v_mov_b32_e32 v41, v4
	v_mov_b32_e32 v42, v4
	v_mov_b32_e32 v43, v4
	v_mov_b32_e32 v48, v4
	v_mov_b32_e32 v49, v4
	v_mov_b32_e32 v50, v4
	v_mov_b32_e32 v51, v4
	v_mov_b32_e32 v60, v4
	v_mov_b32_e32 v61, v4
	v_mov_b32_e32 v62, v4
	v_mov_b32_e32 v63, v4
	v_mov_b32_e32 v64, v4
	v_mov_b32_e32 v65, v4
	v_mov_b32_e32 v66, v4
	v_mov_b32_e32 v67, v4
	v_mov_b32_e32 v76, v4
	v_mov_b32_e32 v77, v4
	v_mov_b32_e32 v78, v4
	v_mov_b32_e32 v79, v4
	v_mov_b32_e32 v80, v4
	v_mov_b32_e32 v81, v4
	v_mov_b32_e32 v82, v4
	v_mov_b32_e32 v83, v4
	v_mov_b32_e32 v84, v4
	v_mov_b32_e32 v85, v4
	v_mov_b32_e32 v86, v4
	v_mov_b32_e32 v87, v4
	v_mov_b32_e32 v88, v4
	v_mov_b32_e32 v89, v4
	v_mov_b32_e32 v90, v4
	v_mov_b32_e32 v91, v4
	v_mov_b32_e32 v100, v4
	v_mov_b32_e32 v101, v4
	v_mov_b32_e32 v102, v4
	v_mov_b32_e32 v103, v4
	v_mov_b32_e32 v104, v4
	v_mov_b32_e32 v105, v4
	v_mov_b32_e32 v106, v4
	v_mov_b32_e32 v107, v4
	v_mov_b32_e32 v116, v4
	v_mov_b32_e32 v117, v4
	v_mov_b32_e32 v118, v4
	v_mov_b32_e32 v119, v4
	v_mov_b32_e32 v120, v4
	v_mov_b32_e32 v121, v4
	v_mov_b32_e32 v122, v4
	v_mov_b32_e32 v123, v4
	v_mov_b32_e32 v132, v4
	v_mov_b32_e32 v133, v4
	v_mov_b32_e32 v134, v4
	v_mov_b32_e32 v135, v4
	v_mov_b32_e32 v136, v4
	v_mov_b32_e32 v137, v4
	v_mov_b32_e32 v138, v4
	v_mov_b32_e32 v139, v4
	v_mov_b32_e32 v92, v4
	v_mov_b32_e32 v93, v4
	v_mov_b32_e32 v94, v4
	v_mov_b32_e32 v95, v4
	v_mov_b32_e32 v96, v4
	v_mov_b32_e32 v97, v4
	v_mov_b32_e32 v98, v4
	v_mov_b32_e32 v99, v4
	v_mov_b32_e32 v108, v4
	v_mov_b32_e32 v109, v4
	v_mov_b32_e32 v110, v4
	v_mov_b32_e32 v111, v4
	v_mov_b32_e32 v112, v4
	v_mov_b32_e32 v113, v4
	v_mov_b32_e32 v114, v4
	v_mov_b32_e32 v115, v4
	v_mov_b32_e32 v124, v4
	v_mov_b32_e32 v125, v4
	v_mov_b32_e32 v126, v4
	v_mov_b32_e32 v127, v4
	v_mov_b32_e32 v128, v4
	v_mov_b32_e32 v129, v4
	v_mov_b32_e32 v130, v4
	v_mov_b32_e32 v131, v4
	v_mov_b32_e32 v140, v4
	v_mov_b32_e32 v141, v4
	v_mov_b32_e32 v142, v4
	v_mov_b32_e32 v143, v4
	v_mov_b32_e32 v144, v4
	v_mov_b32_e32 v145, v4
	v_mov_b32_e32 v146, v4
	v_mov_b32_e32 v147, v4
	s_nop 0

; template <class Epi, class Sched, bool ALIGN_EPI = false, bool SP2 = false>
; __device__ __forceinline__ void gemm_phase(PG8_LAS unsigned char* lds, const Gemm g, const Sched& S, const Epi& E) {
;     ...
;         const bool has_next = S.next(ui + 1, nxt);
;         const char* nA = has_next ? PG8_UA(nxt) : cA; const char* nB = has_next ? PG8_UB(nxt) : cB;
;         for (int t = 0; t < nt; t += 2) {
;             const bool last = (t == nt - 2);
;             const char* a1 = cA + (size_t)(t + 1) * kstep;
;             const char* a2 = last ? nA : cA + (size_t)(t + 2) * kstep; const char* b2 = last ? nB : cB + (size_t)(t + 2) * kstep;
;             const char* a3 = a2 + kstep; const char* b3 = b2 + kstep;
;     ...
; #pragma unroll
;         for (int a = 0; a < 2; ++a)
; #pragma unroll
;             for (int b = 0; b < 2; ++b)
; #pragma unroll
;                 for (int m = 0; m < 4; ++m)
; #pragma unroll
;                     for (int n = 0; n < 2; ++n) acc[a][b][m][n] = (f32x4){0.f, 0.f, 0.f, 0.f};
.LBB0_2661:
	s_ashr_i32 s45, s44, 31
	s_lshl_b64 s[4:5], s[44:45], 20
	s_add_u32 s46, s64, s4
	s_addc_u32 s47, s65, s5
	s_and_b64 s[4:5], s[38:39], exec
	s_cselect_b32 s4, s47, s51
	s_cselect_b32 s5, s46, s50
	s_ashr_i32 s43, s42, 31
	s_lshl_b64 s[6:7], s[42:43], 20
	s_add_u32 s48, s12, s6
	s_addc_u32 s49, s13, s7
	s_and_b64 s[6:7], s[38:39], exec
	s_cselect_b32 s6, s49, s53
	s_cselect_b32 s7, s48, s52
	s_add_u32 s50, s50, 0x80080
	s_addc_u32 s51, s51, 0
	s_add_u32 s43, s52, 0x100
	v_mov_b32_e32 v4, 0
	s_addc_u32 s45, s53, 0
	s_mov_b32 s70, -2
	v_mov_b32_e32 v5, v4
	v_mov_b32_e32 v6, v4
	v_mov_b32_e32 v7, v4
	v_mov_b32_e32 v8, v4
	v_mov_b32_e32 v9, v4
	v_mov_b32_e32 v10, v4
	v_mov_b32_e32 v11, v4
	v_mov_b32_e32 v20, v4
	v_mov_b32_e32 v21, v4
	v_mov_b32_e32 v22, v4
	v_mov_b32_e32 v23, v4
	v_mov_b32_e32 v24, v4
	v_mov_b32_e32 v25, v4
	v_mov_b32_e32 v26, v4
	v_mov_b32_e32 v27, v4
	v_mov_b32_e32 v36, v4
	v_mov_b32_e32 v37, v4
	v_mov_b32_e32 v38, v4
	v_mov_b32_e32 v39, v4
	v_mov_b32_e32 v40, v4
	v_mov_b32_e32 v41, v4
	v_mov_b32_e32 v42, v4
	v_mov_b32_e32 v43, v4
	v_mov_b32_e32 v52, v4
	v_mov_b32_e32 v53, v4
	v_mov_b32_e32 v54, v4
	v_mov_b32_e32 v55, v4
	v_mov_b32_e32 v56, v4
	v_mov_b32_e32 v57, v4
	v_mov_b32_e32 v58, v4
	v_mov_b32_e32 v59, v4
	v_mov_b32_e32 v12, v4
	v_mov_b32_e32 v13, v4
	v_mov_b32_e32 v14, v4
	v_mov_b32_e32 v15, v4
	v_mov_b32_e32 v16, v4
	v_mov_b32_e32 v17, v4
	v_mov_b32_e32 v18, v4
	v_mov_b32_e32 v19, v4
	v_mov_b32_e32 v28, v4
	v_mov_b32_e32 v29, v4
	v_mov_b32_e32 v30, v4
	v_mov_b32_e32 v31, v4
	v_mov_b32_e32 v32, v4
	v_mov_b32_e32 v33, v4
	v_mov_b32_e32 v34, v4
	v_mov_b32_e32 v35, v4
	v_mov_b32_e32 v44, v4
	v_mov_b32_e32 v45, v4
	v_mov_b32_e32 v46, v4
	v_mov_b32_e32 v47, v4
	v_mov_b32_e32 v48, v4
	v_mov_b32_e32 v49, v4
	v_mov_b32_e32 v50, v4
	v_mov_b32_e32 v51, v4
	v_mov_b32_e32 v60, v4
	v_mov_b32_e32 v61, v4
	v_mov_b32_e32 v62, v4
	v_mov_b32_e32 v63, v4
	v_mov_b32_e32 v64, v4
	v_mov_b32_e32 v65, v4
	v_mov_b32_e32 v66, v4
	v_mov_b32_e32 v67, v4
	v_mov_b32_e32 v68, v4
	v_mov_b32_e32 v69, v4
	v_mov_b32_e32 v70, v4
	v_mov_b32_e32 v71, v4
	v_mov_b32_e32 v72, v4
	v_mov_b32_e32 v73, v4
	v_mov_b32_e32 v74, v4
	v_mov_b32_e32 v75, v4
	v_mov_b32_e32 v84, v4
	v_mov_b32_e32 v85, v4
	v_mov_b32_e32 v86, v4
	v_mov_b32_e32 v87, v4
	v_mov_b32_e32 v88, v4
	v_mov_b32_e32 v89, v4
	v_mov_b32_e32 v90, v4
	v_mov_b32_e32 v91, v4
	v_mov_b32_e32 v100, v4
	v_mov_b32_e32 v101, v4
	v_mov_b32_e32 v102, v4
	v_mov_b32_e32 v103, v4
	v_mov_b32_e32 v104, v4
	v_mov_b32_e32 v105, v4
	v_mov_b32_e32 v106, v4
	v_mov_b32_e32 v107, v4
	v_mov_b32_e32 v116, v4
	v_mov_b32_e32 v117, v4
	v_mov_b32_e32 v118, v4
	v_mov_b32_e32 v119, v4
	v_mov_b32_e32 v120, v4
	v_mov_b32_e32 v121, v4
	v_mov_b32_e32 v122, v4
	v_mov_b32_e32 v123, v4
	v_mov_b32_e32 v76, v4
	v_mov_b32_e32 v77, v4
	v_mov_b32_e32 v78, v4
	v_mov_b32_e32 v79, v4
	v_mov_b32_e32 v80, v4
	v_mov_b32_e32 v81, v4
	v_mov_b32_e32 v82, v4
	v_mov_b32_e32 v83, v4
	v_mov_b32_e32 v92, v4
	v_mov_b32_e32 v93, v4
	v_mov_b32_e32 v94, v4
	v_mov_b32_e32 v95, v4
	v_mov_b32_e32 v96, v4
	v_mov_b32_e32 v97, v4
	v_mov_b32_e32 v98, v4
	v_mov_b32_e32 v99, v4
	v_mov_b32_e32 v108, v4
	v_mov_b32_e32 v109, v4
	v_mov_b32_e32 v110, v4
	v_mov_b32_e32 v111, v4
	v_mov_b32_e32 v112, v4
	v_mov_b32_e32 v113, v4
	v_mov_b32_e32 v114, v4
	v_mov_b32_e32 v115, v4
	v_mov_b32_e32 v124, v4
	v_mov_b32_e32 v125, v4
	v_mov_b32_e32 v126, v4
	v_mov_b32_e32 v127, v4
	v_mov_b32_e32 v128, v4
	v_mov_b32_e32 v129, v4
	v_mov_b32_e32 v130, v4
	v_mov_b32_e32 v131, v4
	s_nop 0
	s_nop 0
	s_nop 0
	s_nop 0
	s_nop 0
	s_nop 0
	s_nop 0
	s_nop 0
	s_nop 0
	s_nop 0
	s_nop 0
	s_nop 0
	s_nop 0
	s_nop 0
	s_nop 0

; template <class Epi, class Sched, bool ALIGN_EPI = false, bool SP2 = false>
; __device__ __forceinline__ void gemm_phase(PG8_LAS unsigned char* lds, const Gemm g, const Sched& S, const Epi& E) {
;     ...
;         const bool has_next = S.next(ui + 1, nxt);
;         const char* nA = has_next ? PG8_UA(nxt) : cA; const char* nB = has_next ? PG8_UB(nxt) : cB;
;         for (int t = 0; t < nt; t += 2) {
;             const bool last = (t == nt - 2);
;             const char* a1 = cA + (size_t)(t + 1) * kstep;
;             const char* a2 = last ? nA : cA + (size_t)(t + 2) * kstep; const char* b2 = last ? nB : cB + (size_t)(t + 2) * kstep;
;             const char* a3 = a2 + kstep; const char* b3 = b2 + kstep;
;     ...
; #pragma unroll
;         for (int a = 0; a < 2; ++a)
; #pragma unroll
;             for (int b = 0; b < 2; ++b)
; #pragma unroll
;                 for (int m = 0; m < 4; ++m)
; #pragma unroll
;                     for (int n = 0; n < 2; ++n) acc[a][b][m][n] = (f32x4){0.f, 0.f, 0.f, 0.f};
.LBB0_2769:
	s_add_u32 s4, s50, 0x100
	v_mov_b32_e32 v4, 0
	s_addc_u32 s5, s51, 0
	s_mov_b32 s6, -2
	s_waitcnt lgkmcnt(0)
	v_mov_b32_e32 v5, v4
	v_mov_b32_e32 v6, v4
	v_mov_b32_e32 v7, v4
	v_mov_b32_e32 v8, v4
	v_mov_b32_e32 v9, v4
	v_mov_b32_e32 v10, v4
	v_mov_b32_e32 v11, v4
	v_mov_b32_e32 v20, v4
	v_mov_b32_e32 v21, v4
	v_mov_b32_e32 v22, v4
	v_mov_b32_e32 v23, v4
	v_mov_b32_e32 v24, v4
	v_mov_b32_e32 v25, v4
	v_mov_b32_e32 v26, v4
	v_mov_b32_e32 v27, v4
	v_mov_b32_e32 v36, v4
	v_mov_b32_e32 v37, v4
	v_mov_b32_e32 v38, v4
	v_mov_b32_e32 v39, v4
	v_mov_b32_e32 v40, v4
	v_mov_b32_e32 v41, v4
	v_mov_b32_e32 v42, v4
	v_mov_b32_e32 v43, v4
	v_mov_b32_e32 v52, v4
	v_mov_b32_e32 v53, v4
	v_mov_b32_e32 v54, v4
	v_mov_b32_e32 v55, v4
	v_mov_b32_e32 v56, v4
	v_mov_b32_e32 v57, v4
	v_mov_b32_e32 v58, v4
	v_mov_b32_e32 v59, v4
	v_mov_b32_e32 v12, v4
	v_mov_b32_e32 v13, v4
	v_mov_b32_e32 v14, v4
	v_mov_b32_e32 v15, v4
	v_mov_b32_e32 v16, v4
	v_mov_b32_e32 v17, v4
	v_mov_b32_e32 v18, v4
	v_mov_b32_e32 v19, v4
	v_mov_b32_e32 v28, v4
	v_mov_b32_e32 v29, v4
	v_mov_b32_e32 v30, v4
	v_mov_b32_e32 v31, v4
	v_mov_b32_e32 v32, v4
	v_mov_b32_e32 v33, v4
	v_mov_b32_e32 v34, v4
	v_mov_b32_e32 v35, v4
	v_mov_b32_e32 v44, v4
	v_mov_b32_e32 v45, v4
	v_mov_b32_e32 v46, v4
	v_mov_b32_e32 v47, v4
	v_mov_b32_e32 v48, v4
	v_mov_b32_e32 v49, v4
	v_mov_b32_e32 v50, v4
	v_mov_b32_e32 v51, v4
	v_mov_b32_e32 v60, v4
	v_mov_b32_e32 v61, v4
	v_mov_b32_e32 v62, v4
	v_mov_b32_e32 v63, v4
	v_mov_b32_e32 v64, v4
	v_mov_b32_e32 v65, v4
	v_mov_b32_e32 v66, v4
	v_mov_b32_e32 v67, v4
	v_mov_b32_e32 v68, v4
	v_mov_b32_e32 v69, v4
	v_mov_b32_e32 v70, v4
	v_mov_b32_e32 v71, v4
	v_mov_b32_e32 v72, v4
	v_mov_b32_e32 v73, v4
	v_mov_b32_e32 v74, v4
	v_mov_b32_e32 v75, v4
	v_mov_b32_e32 v84, v4
	v_mov_b32_e32 v85, v4
	v_mov_b32_e32 v86, v4
	v_mov_b32_e32 v87, v4
	v_mov_b32_e32 v88, v4
	v_mov_b32_e32 v89, v4
	v_mov_b32_e32 v90, v4
	v_mov_b32_e32 v91, v4
	v_mov_b32_e32 v100, v4
	v_mov_b32_e32 v101, v4
	v_mov_b32_e32 v102, v4
	v_mov_b32_e32 v103, v4
	v_mov_b32_e32 v104, v4
	v_mov_b32_e32 v105, v4
	v_mov_b32_e32 v106, v4
	v_mov_b32_e32 v107, v4
	v_mov_b32_e32 v116, v4
	v_mov_b32_e32 v117, v4
	v_mov_b32_e32 v118, v4
	v_mov_b32_e32 v119, v4
	v_mov_b32_e32 v120, v4
	v_mov_b32_e32 v121, v4
	v_mov_b32_e32 v122, v4
	v_mov_b32_e32 v123, v4
	v_mov_b32_e32 v76, v4
	v_mov_b32_e32 v77, v4
	v_mov_b32_e32 v78, v4
	v_mov_b32_e32 v79, v4
	v_mov_b32_e32 v80, v4
	v_mov_b32_e32 v81, v4
	v_mov_b32_e32 v82, v4
	v_mov_b32_e32 v83, v4
	v_mov_b32_e32 v92, v4
	v_mov_b32_e32 v93, v4
	v_mov_b32_e32 v94, v4
	v_mov_b32_e32 v95, v4
	v_mov_b32_e32 v96, v4
	v_mov_b32_e32 v97, v4
	v_mov_b32_e32 v98, v4
	v_mov_b32_e32 v99, v4
	v_mov_b32_e32 v108, v4
	v_mov_b32_e32 v109, v4
	v_mov_b32_e32 v110, v4
	v_mov_b32_e32 v111, v4
	v_mov_b32_e32 v112, v4
	v_mov_b32_e32 v113, v4
	v_mov_b32_e32 v114, v4
	v_mov_b32_e32 v115, v4
	v_mov_b32_e32 v124, v4
	v_mov_b32_e32 v125, v4
	v_mov_b32_e32 v126, v4
	v_mov_b32_e32 v127, v4
	v_mov_b32_e32 v128, v4
	v_mov_b32_e32 v129, v4
	v_mov_b32_e32 v130, v4
	v_mov_b32_e32 v131, v4
	s_nop 0
	s_nop 0
	s_nop 0
	s_nop 0
	s_nop 0
	s_nop 0
	s_nop 0
	s_nop 0
	s_nop 0
